# engine carries w_up + all of w_gate (43 items/wave); P4 keeps the embedded conversion of w_up_pool/w_up_hgrn/w_out only (no g_ffn chains)
# speedup vs baseline: 1.0123x; 1.0123x over previous
; __global__ void __launch_bounds__(NWAVES * 64, 2) fwd(Args args) {
;     ...
;             p0_transpose_matrix(w_gate, D, DFF, WguT, D, 1, scr, gw, NGW, F.lane, g_ffn);
;         }
;         p0_transpose_matrix(w_up, D, DFF, WguT, D, 2, scr, gw, NGW, F.lane, g_ffn);
.LBB0_143:
	s_add_i32 s32, s32, 1
	s_mov_b32 s97, 0
	s_cmp_lt_i32 s32, 1
	s_cbranch_scc1 .Leng_done
	s_sub_i32 s93, s32, 1
	s_and_b32 s93, s93, 3
	s_cmp_lg_u32 s93, 0
	s_cbranch_scc1 .Leng_not0
	s_mov_b64 s[100:101], 0
	s_bitcmp1_b32 s85, 31
	s_cbranch_scc1 .Leng_grpB
	s_lshr_b32 s93, s85, 16
	s_cmp_ge_u32 s93, 0x100
	s_cbranch_scc1 .Leng_done
	s_cmp_lt_u32 s93, 0x80
	s_cbranch_scc0 .Leng_gate
	v_readlane_b32 s98, v245, 2
	v_readlane_b32 s99, v245, 3
	s_movk_i32 s100, 0x80
	s_branch .Leng_mat

;     ...
;         const int cga = (2 * blk) * 2048 + cvslot, cgb = cga + 2048; const bool cva_on = FULL && cv && cga < CV_TOTAL, cvb_on = FULL && cv && cgb < CV_TOTAL;
;         if (cva_on) { cia = conv_decode(cv, cga); conv_load(cia, lane, cva); }
;         if (cvb_on) { cib = conv_decode(cv, cgb); conv_load(cib, lane, cvb); }
.LBB0_558:
	s_add_i32 s26, s89, 0xfffff000
	s_cmp_lt_i32 s26, 0x8000
	s_cselect_b64 s[0:1], -1, 0
	s_and_b64 s[0:1], s[34:35], s[0:1]
	v_cndmask_b32_e64 v66, 0, 1, s[0:1]
	v_cmp_ne_u32_e64 s[30:31], 1, v66
	s_andn2_b64 vcc, exec, s[0:1]
	s_cbranch_vccnz .LBB0_567
	s_cmpk_gt_i32 s26, 0x1fff
	s_cselect_b64 s[0:1], -1, 0
	s_cmpk_gt_i32 s26, 0x3fff
	v_cndmask_b32_e64 v66, 0, 1, s[0:1]
	s_cselect_b64 s[0:1], -1, 0
	s_cmpk_gt_i32 s26, 0x7fff
	v_cndmask_b32_e64 v67, 0, 1, s[0:1]
	s_cselect_b64 s[0:1], -1, 0
	v_readfirstlane_b32 s20, v66
	v_readfirstlane_b32 s21, v67
	s_cmp_lg_u64 s[0:1], 0
	s_addc_u32 s27, s20, s21
	s_cmp_lt_i32 s27, 1
	s_mov_b32 s28, s27
	s_cbranch_scc1 .LBB0_564
	s_cmp_eq_u32 s27, 1
	s_mov_b64 s[0:1], -1
	s_cbranch_scc1 .LBB0_562
	s_cmp_eq_u32 s27, 2
	s_cselect_b32 s28, s84, 0xffff8000
	s_mov_b64 s[0:1], 0

;     ...
;         const int cga = (2 * blk) * 2048 + cvslot, cgb = cga + 2048; const bool cva_on = FULL && cv && cga < CV_TOTAL, cvb_on = FULL && cv && cgb < CV_TOTAL;
;         if (cva_on) { cia = conv_decode(cv, cga); conv_load(cia, lane, cva); }
;         if (cvb_on) { cib = conv_decode(cv, cgb); conv_load(cib, lane, cvb); }
.LBB0_567:
.LBB0_568:
	s_cmp_lt_i32 s26, 0x7800
	s_cselect_b64 s[0:1], -1, 0
	s_and_b64 s[0:1], s[34:35], s[0:1]
	v_cndmask_b32_e64 v66, 0, 1, s[0:1]
	v_cmp_ne_u32_e64 s[28:29], 1, v66
	s_andn2_b64 vcc, exec, s[0:1]
	s_cbranch_vccnz .LBB0_577
	s_cmpk_gt_i32 s26, 0x17ff
	s_cselect_b64 s[0:1], -1, 0
	s_cmpk_gt_i32 s26, 0x37ff
	v_cndmask_b32_e64 v66, 0, 1, s[0:1]
	s_cselect_b64 s[0:1], -1, 0
	s_cmpk_gt_i32 s26, 0x77ff
	v_cndmask_b32_e64 v67, 0, 1, s[0:1]
	s_cselect_b64 s[0:1], -1, 0
	v_readfirstlane_b32 s20, v66
	v_readfirstlane_b32 s21, v67
	s_cmp_lg_u64 s[0:1], 0
	s_addc_u32 s26, s20, s21
	s_cmp_lt_i32 s26, 1
	s_mov_b32 s27, s26
	s_cbranch_scc1 .LBB0_574
	s_cmp_eq_u32 s26, 1
	s_mov_b64 s[0:1], -1
	s_cbranch_scc1 .LBB0_572
	s_cmp_eq_u32 s26, 2
	s_cselect_b32 s27, s84, 0xffff8000
	s_mov_b64 s[0:1], 0

;     ...
;         const int cga = (2 * blk) * 2048 + cvslot, cgb = cga + 2048; const bool cva_on = FULL && cv && cga < CV_TOTAL, cvb_on = FULL && cv && cgb < CV_TOTAL;
;         if (cva_on) { cia = conv_decode(cv, cga); conv_load(cia, lane, cva); }
;         if (cvb_on) { cib = conv_decode(cv, cgb); conv_load(cib, lane, cvb); }
.LBB0_604:
	s_cmp_lt_i32 s89, 0x8000
	s_cselect_b64 s[0:1], -1, 0
	s_and_b64 s[0:1], s[34:35], s[0:1]
	v_cndmask_b32_e64 v66, 0, 1, s[0:1]
	v_cmp_ne_u32_e64 s[30:31], 1, v66
	s_andn2_b64 vcc, exec, s[0:1]
	s_cbranch_vccnz .LBB0_613
	s_cmpk_gt_i32 s89, 0x1fff
	s_cselect_b64 s[0:1], -1, 0
	s_cmpk_gt_i32 s89, 0x3fff
	v_cndmask_b32_e64 v66, 0, 1, s[0:1]
	s_cselect_b64 s[0:1], -1, 0
	s_cmpk_gt_i32 s89, 0x7fff
	v_cndmask_b32_e64 v67, 0, 1, s[0:1]
	s_cselect_b64 s[0:1], -1, 0
	v_readfirstlane_b32 s20, v66
	v_readfirstlane_b32 s21, v67
	s_cmp_lg_u64 s[0:1], 0
	s_addc_u32 s28, s20, s21
	s_cmp_lt_i32 s28, 1
	s_mov_b32 s29, s28
	s_cbranch_scc1 .LBB0_610
	s_cmp_eq_u32 s28, 1
	s_mov_b64 s[0:1], -1
	s_cbranch_scc1 .LBB0_608
	s_cmp_eq_u32 s28, 2
	s_cselect_b32 s29, s84, 0xffff8000
	s_mov_b64 s[0:1], 0

;     ...
;         const int cga = (2 * blk) * 2048 + cvslot, cgb = cga + 2048; const bool cva_on = FULL && cv && cga < CV_TOTAL, cvb_on = FULL && cv && cgb < CV_TOTAL;
;         if (cva_on) { cia = conv_decode(cv, cga); conv_load(cia, lane, cva); }
;         if (cvb_on) { cib = conv_decode(cv, cgb); conv_load(cib, lane, cvb); }
.LBB0_613:
.LBB0_614:
	s_cmp_lt_i32 s89, 0x7800
	s_cselect_b64 s[20:21], -1, 0
	s_and_b64 s[20:21], s[34:35], s[20:21]
	v_cndmask_b32_e64 v66, 0, 1, s[20:21]
	v_cmp_ne_u32_e64 s[28:29], 1, v66
	s_andn2_b64 vcc, exec, s[20:21]
	s_cbranch_vccnz .LBB0_623
	s_cmpk_gt_i32 s89, 0x17ff
	s_cselect_b64 s[20:21], -1, 0
	s_cmpk_gt_i32 s89, 0x37ff
	v_cndmask_b32_e64 v66, 0, 1, s[20:21]
	s_cselect_b64 s[20:21], -1, 0
	s_cmpk_gt_i32 s89, 0x77ff
	v_cndmask_b32_e64 v67, 0, 1, s[20:21]
	s_cselect_b64 s[20:21], -1, 0
	v_readfirstlane_b32 s37, v66
	v_readfirstlane_b32 s72, v67
	s_cmp_lg_u64 s[20:21], 0
	s_addc_u32 s37, s37, s72
	s_cmp_lt_i32 s37, 1
	s_mov_b32 s77, s37
	s_cbranch_scc1 .LBB0_620
	s_cmp_eq_u32 s37, 1
	s_mov_b64 s[72:73], -1
	s_cbranch_scc1 .LBB0_618
	s_cmp_eq_u32 s37, 2
	s_cselect_b32 s77, s84, 0xffff8000
	s_mov_b64 s[72:73], 0
